# mixer_pre gates stage: 16 gate-GEMM weight-fragment loads issued together before the barrier with counted vmcnt; bias loads of groups 2-4 issued with group 1
# speedup vs baseline: 1.0130x; 1.0049x over previous
; #define LAS __attribute__((address_space(3)))
; __device__ __forceinline__ float bf2f(unsigned short b) { return __uint_as_float(((unsigned)b) << 16); }
; __device__ __forceinline__ unsigned short f2bf(float f) { return (unsigned short)(pg8::cvt_pk_bf16(f, 0.f) & 0xffffu); }
; __device__ __forceinline__ void mixer_pre_item(int item, const float* const* in, int l, unsigned char* ws, LAS unsigned char* lds, int tid, int lane, int wave) {
;     ...
;         const int ch = tid & 255, t0 = (tid >> 8) * 16;
;         const float* cw = in[8] + (size_t)l * 4 * 256;
;         const float w0 = cw[ch], w1 = cw[256 + ch], w2 = cw[512 + ch], w3 = cw[768 + ch], bb = in[9][l * 256 + ch];
;         float xm3 = bf2f(STGL[t0 * 256 + ch]), xm2 = bf2f(STGL[(t0 + 1) * 256 + ch]), xm1 = bf2f(STGL[(t0 + 2) * 256 + ch]);
; #pragma unroll 8
;         for (int i = 0; i < 16; ++i) { const float xc = bf2f(STGL[(t0 + i + 3) * 256 + ch]); const float xr = w0 * xm3 + w1 * xm2 + w2 * xm1 + w3 * xc + bb;
;             XRF[(t0 + i) * 256 + ch] = xr; XRB[(t0 + i) * 264 + ch] = f2bf(xr); xm3 = xm2; xm2 = xm1; xm1 = xc; }
;     }
;     __syncthreads();
;     {
;         const int hb = wave & 3, mf = wave >> 2, fr = lane & 15, q = lane >> 4;
;         const bf16_t* WTa = (const bf16_t*)(ws + WS_W + (size_t)l * W_LAYER + O_LRU) + hb * 4096;
;         const bf16_t* WTx = WTa + 16384;
;         f32x4 aa[4], ax[4];
; #pragma unroll
;         for (int nf = 0; nf < 4; ++nf) { aa[nf] = (f32x4){0.f, 0.f, 0.f, 0.f}; ax[nf] = (f32x4){0.f, 0.f, 0.f, 0.f}; }
; #pragma unroll
;         for (int ks = 0; ks < 2; ++ks) {
;             const bf16x8 A = *(const LAS bf16x8*)(XRB + (16 * mf + fr) * 264 + 64 * hb + 32 * ks + 8 * q);
; #pragma unroll
;             for (int nf = 0; nf < 4; ++nf) {
;                 const bf16x8 Ba = *(const bf16x8*)(WTa + (16 * nf + fr) * 64 + 32 * ks + 8 * q), Bx = *(const bf16x8*)(WTx + (16 * nf + fr) * 64 + 32 * ks + 8 * q);
.LBB0_640:
	v_add_u32_e32 v12, 0, v8
	ds_read_u16 v13, v12
	v_mul_f32_e32 v14, v5, v10
	v_fmac_f32_e32 v14, v4, v11
	v_fmac_f32_e32 v14, v6, v9
	v_add_u32_e32 v15, 0, v2
	s_waitcnt lgkmcnt(0)
	v_lshlrev_b32_e32 v13, 16, v13
	v_fmac_f32_e32 v14, v7, v13
	s_waitcnt vmcnt(0)
	v_add_f32_e32 v11, v0, v14
	v_add_u32_e32 v14, 0, v3
	v_add_u32_e32 v16, 0x14600, v15
	ds_write_b32 v14, v11
	v_cvt_pk_bf16_f32 v11, v11, v1
	ds_write_b16 v16, v11
	ds_read_u16 v11, v12 offset:512
	v_mul_f32_e32 v16, v5, v9
	v_fmac_f32_e32 v16, v4, v10
	v_fmac_f32_e32 v16, v6, v13
	s_add_i32 s20, s20, -8
	s_waitcnt lgkmcnt(0)
	v_lshlrev_b32_e32 v11, 16, v11
	v_fmac_f32_e32 v16, v7, v11
	v_add_f32_e32 v10, v0, v16
	v_add_u32_e32 v16, 0x14810, v15
	ds_write_b32 v14, v10 offset:1024
	v_cvt_pk_bf16_f32 v10, v10, v1
	ds_write_b16 v16, v10
	ds_read_u16 v10, v12 offset:1024
	v_mul_f32_e32 v16, v5, v13
	v_fmac_f32_e32 v16, v4, v9
	v_fmac_f32_e32 v16, v6, v11
	v_add_u32_e32 v2, 0x1080, v2
	s_waitcnt lgkmcnt(0)
	v_lshlrev_b32_e32 v10, 16, v10
	v_fmac_f32_e32 v16, v7, v10
	v_add_f32_e32 v9, v0, v16
	v_add_u32_e32 v16, 0x14a20, v15
	ds_write_b32 v14, v9 offset:2048
	v_cvt_pk_bf16_f32 v9, v9, v1
	ds_write_b16 v16, v9
	ds_read_u16 v9, v12 offset:1536
	v_mul_f32_e32 v16, v5, v11
	v_fmac_f32_e32 v16, v4, v13
	v_fmac_f32_e32 v16, v6, v10
	v_add_u32_e32 v3, 0x2000, v3
	s_waitcnt lgkmcnt(0)
	v_lshlrev_b32_e32 v9, 16, v9
	v_fmac_f32_e32 v16, v7, v9
	v_add_f32_e32 v13, v0, v16
	v_add_u32_e32 v16, 0x14c30, v15
	ds_write_b32 v14, v13 offset:3072
	v_cvt_pk_bf16_f32 v13, v13, v1
	ds_write_b16 v16, v13
	ds_read_u16 v13, v12 offset:2048
	v_mul_f32_e32 v16, v5, v10
	v_fmac_f32_e32 v16, v4, v11
	v_fmac_f32_e32 v16, v6, v9
	v_add_u32_e32 v8, 0x1000, v8
	s_waitcnt lgkmcnt(0)
	v_lshlrev_b32_e32 v13, 16, v13
	v_fmac_f32_e32 v16, v7, v13
	v_add_f32_e32 v11, v0, v16
	v_add_u32_e32 v16, 0x14e40, v15
	ds_write_b32 v14, v11 offset:4096
	v_cvt_pk_bf16_f32 v11, v11, v1
	ds_write_b16 v16, v11
	ds_read_u16 v11, v12 offset:2560
	v_mul_f32_e32 v16, v5, v9
	v_fmac_f32_e32 v16, v4, v10
	v_fmac_f32_e32 v16, v6, v13
	s_cmp_eq_u32 s20, 0
	s_waitcnt lgkmcnt(0)
	v_lshlrev_b32_e32 v11, 16, v11
	v_fmac_f32_e32 v16, v7, v11
	v_add_f32_e32 v10, v0, v16
	v_add_u32_e32 v16, 0x15050, v15
	ds_write_b32 v14, v10 offset:5120
	v_cvt_pk_bf16_f32 v10, v10, v1
	ds_write_b16 v16, v10
	ds_read_u16 v10, v12 offset:3072
	v_mul_f32_e32 v16, v5, v13
	v_fmac_f32_e32 v16, v4, v9
	v_fmac_f32_e32 v16, v6, v11
	s_waitcnt lgkmcnt(0)
	v_lshlrev_b32_e32 v10, 16, v10
	v_fmac_f32_e32 v16, v7, v10
	v_add_f32_e32 v9, v0, v16
	v_add_u32_e32 v16, 0x15260, v15
	ds_write_b32 v14, v9 offset:6144
	v_cvt_pk_bf16_f32 v9, v9, v1
	ds_write_b16 v16, v9
	ds_read_u16 v9, v12 offset:3584
	v_mul_f32_e32 v12, v5, v11
	v_fmac_f32_e32 v12, v4, v13
	v_fmac_f32_e32 v12, v6, v10
	v_add_u32_e32 v13, 0x15470, v15
	s_waitcnt lgkmcnt(0)
	v_lshlrev_b32_e32 v9, 16, v9
	v_fmac_f32_e32 v12, v7, v9
	v_add_f32_e32 v12, v0, v12
	ds_write_b32 v14, v12 offset:7168
	v_cvt_pk_bf16_f32 v12, v12, v1
	ds_write_b16 v13, v12
	s_cbranch_scc0 .LBB0_640
	s_bfe_u32 s20, s15, 0x20006
	s_lshl_b32 s21, s20, 13
	s_add_u32 s30, s6, s21
	s_addc_u32 s31, s7, 0
	s_ashr_i32 s15, s15, 4
	v_bfi_b32 v0, -16, s15, v34
	s_movk_i32 s21, 0x210
	v_mul_lo_u32 v2, v0, s21
	s_lshl_b32 s21, s20, 7
	s_add_i32 s21, s21, 0
	v_and_b32_e32 v62, 15, v34
	s_add_i32 s21, s21, 0x14600
	v_and_b32_e32 v0, 48, v35
	v_add3_u32 v48, s21, v2, v0
	v_lshl_add_u64 v[30:31], s[30:31], 0, v[0:1]
	s_mov_b64 s[30:31], 0x8000
	v_lshlrev_b32_e32 v0, 7, v62
	v_lshl_add_u64 v[32:33], v[30:31], 0, s[30:31]
	v_or_b32_e32 v56, 0x1000, v0
	v_mov_b32_e32 v57, v1
	v_lshl_add_u64 v[52:53], v[30:31], 0, v[0:1]
	v_lshl_add_u64 v[54:55], v[32:33], 0, v[0:1]
	v_lshl_add_u64 v[22:23], v[30:31], 0, v[56:57]
	v_lshl_add_u64 v[26:27], v[32:33], 0, v[56:57]
	global_load_dwordx4 v[108:111], v[52:53], off offset:2048
	global_load_dwordx4 v[112:115], v[22:23], off
	global_load_dwordx4 v[116:119], v[26:27], off
	global_load_dwordx4 v[120:123], v[52:53], off
	global_load_dwordx4 v[124:127], v[54:55], off
	global_load_dwordx4 v[128:131], v[54:55], off offset:2048
	global_load_dwordx4 v[132:135], v[22:23], off offset:2048
	global_load_dwordx4 v[136:139], v[26:27], off offset:2048
	global_load_dwordx4 v[140:143], v[52:53], off offset:64
	global_load_dwordx4 v[144:147], v[54:55], off offset:64
	global_load_dwordx4 v[148:151], v[52:53], off offset:2112
	global_load_dwordx4 v[152:155], v[54:55], off offset:2112
	global_load_dwordx4 v[168:171], v[22:23], off offset:64
	global_load_dwordx4 v[172:175], v[26:27], off offset:64
	global_load_dwordx4 v[176:179], v[26:27], off offset:2112
	global_load_dwordx4 v[180:183], v[22:23], off offset:2112
	s_waitcnt lgkmcnt(0)
	s_barrier
; #define LAS __attribute__((address_space(3)))
; __device__ __forceinline__ float sigmoidf_(float x) { return __builtin_amdgcn_rcpf(1.0f + __expf(-x)); }
; __device__ __forceinline__ float softplusf_(float x) { const float e = __expf(-fabsf(x)); const float lg = (e < 0.03f) ? e * (1.0f - e * (0.5f - e * (0.33333334f - 0.25f * e))) : __logf(1.0f + e); return fmaxf(x, 0.f) + lg; }
; #define MFMA16(a, b, c) __builtin_amdgcn_mfma_f32_16x16x32_bf16((a), (b), (c), 0, 0, 0)
; __device__ __forceinline__ void mixer_pre_item(int item, const float* const* in, int l, unsigned char* ws, LAS unsigned char* lds, int tid, int lane, int wave) {
;     ...
;             const bf16x8 A = *(const LAS bf16x8*)(XRB + (16 * mf + fr) * 264 + 64 * hb + 32 * ks + 8 * q);
; #pragma unroll
;             for (int nf = 0; nf < 4; ++nf) {
;                 const bf16x8 Ba = *(const bf16x8*)(WTa + (16 * nf + fr) * 64 + 32 * ks + 8 * q), Bx = *(const bf16x8*)(WTx + (16 * nf + fr) * 64 + 32 * ks + 8 * q);
;                 aa[nf] = MFMA16(A, Ba, aa[nf]); ax[nf] = MFMA16(A, Bx, ax[nf]); }
;         }
; #pragma unroll
;         for (int nf = 0; nf < 4; ++nf) {
;             const int ch = 64 * hb + 16 * nf + fr;
;             const float ba = in[11][l * 256 + ch], bx = in[13][l * 256 + ch], sp = softplusf_(-in[14][l * 256 + ch]);
; #pragma unroll
;             for (int jj = 0; jj < 4; ++jj) { const int tok = 16 * mf + 4 * q + jj;
;                 const float r = sigmoidf_(aa[nf][jj] + ba), ig = sigmoidf_(ax[nf][jj] + bx), la = -8.0f * r * sp, a = __expf(la), x2 = 2.0f * la;
;                 const float om = (x2 > -0.25f) ? -x2 * (1.0f + x2 * (0.5f + x2 * (0.16666667f + x2 * (0.041666668f + x2 * (0.008333334f + x2 * 0.0013888889f))))) : 1.0f - a * a;
;                 const float mult = sqrtf(om);
	ds_read_b128 v[2:5], v48
	v_or_b32_e32 v0, 0x1800, v0
	ds_read_b128 v[48:51], v48 offset:64
	s_mov_b64 s[30:31], 0x8040
	v_lshl_add_u64 v[58:59], v[30:31], 0, 64
	v_lshl_add_u64 v[60:61], v[30:31], 0, s[30:31]
	v_readlane_b32 s48, v248, 55
	v_readlane_b32 s49, v248, 56
	v_readlane_b32 s50, v248, 57
	v_readlane_b32 s51, v248, 58
	v_readlane_b32 s52, v248, 59
	v_readlane_b32 s53, v248, 60
	v_readlane_b32 s54, v248, 61
	v_readlane_b32 s55, v248, 62
	v_readlane_b32 s56, v248, 63
	v_readlane_b32 s57, v250, 0
	v_readlane_b32 s58, v250, 1
	v_readlane_b32 s59, v250, 2
	v_readlane_b32 s60, v250, 3
	v_readlane_b32 s61, v250, 4
	v_readlane_b32 s62, v250, 5
	v_readlane_b32 s63, v250, 6
	s_waitcnt vmcnt(15) lgkmcnt(1)
	v_mfma_f32_16x16x32_bf16 v[14:17], v[2:5], v[108:111], 0
	s_waitcnt vmcnt(14)
	v_mfma_f32_16x16x32_bf16 v[36:39], v[2:5], v[112:115], 0
	s_waitcnt vmcnt(13)
	v_mfma_f32_16x16x32_bf16 v[40:43], v[2:5], v[116:119], 0
	s_waitcnt vmcnt(12)
	v_mfma_f32_16x16x32_bf16 v[6:9], v[2:5], v[120:123], 0
	s_waitcnt vmcnt(11)
	v_mfma_f32_16x16x32_bf16 v[10:13], v[2:5], v[124:127], 0
	s_waitcnt vmcnt(10)
	v_mfma_f32_16x16x32_bf16 v[18:21], v[2:5], v[128:131], 0
	s_waitcnt vmcnt(9)
	v_mfma_f32_16x16x32_bf16 v[44:47], v[2:5], v[132:135], 0
	s_waitcnt vmcnt(8)
	v_mfma_f32_16x16x32_bf16 v[2:5], v[2:5], v[136:139], 0
	s_waitcnt vmcnt(7) lgkmcnt(0)
	v_mfma_f32_16x16x32_bf16 v[30:33], v[48:51], v[140:143], v[6:9]
	s_waitcnt vmcnt(6)
	v_mfma_f32_16x16x32_bf16 v[26:29], v[48:51], v[144:147], v[10:13]
	s_waitcnt vmcnt(5)
	v_mfma_f32_16x16x32_bf16 v[22:25], v[48:51], v[148:151], v[14:17]
	s_waitcnt vmcnt(4)
	v_mfma_f32_16x16x32_bf16 v[18:21], v[48:51], v[152:155], v[18:21]
	s_waitcnt vmcnt(3)
	v_mfma_f32_16x16x32_bf16 v[14:17], v[48:51], v[168:171], v[36:39]
	s_waitcnt vmcnt(2)
	v_mfma_f32_16x16x32_bf16 v[10:13], v[48:51], v[172:175], v[40:43]
	s_waitcnt vmcnt(1)
	v_mfma_f32_16x16x32_bf16 v[2:5], v[48:51], v[176:179], v[2:5]
	v_lshl_or_b32 v36, s20, 6, v62
	v_or_b32_e32 v0, s1, v36
	v_readlane_b32 s20, v248, 51
	v_lshlrev_b64 v[38:39], 2, v[0:1]
	v_readlane_b32 s21, v248, 52
	s_waitcnt vmcnt(0)
	v_mfma_f32_16x16x32_bf16 v[6:9], v[48:51], v[180:183], v[44:47]
	s_nop 0
	v_lshl_add_u64 v[40:41], s[20:21], 0, v[38:39]
	v_lshl_add_u64 v[76:77], s[20:21], 0, v[38:39]
	global_load_dword v37, v[40:41], off
	v_lshl_add_u64 v[40:41], s[48:49], 0, v[38:39]
	v_lshl_add_u64 v[74:75], s[50:51], 0, v[38:39]
	v_lshl_add_u64 v[38:39], s[50:51], 0, v[38:39]
	global_load_dword v38, v[38:39], off
	s_mov_b32 s20, 0xbfb8aa3b
	global_load_dword v0, v[40:41], off
	global_load_dword v70, v[74:75], off offset:64
	global_load_dword v64, v[76:77], off offset:64
	global_load_dword v67, v[40:41], off offset:64
	global_load_dword v71, v[74:75], off offset:128
	global_load_dword v65, v[76:77], off offset:128
	global_load_dword v68, v[40:41], off offset:128
	global_load_dword v72, v[74:75], off offset:192
	global_load_dword v66, v[76:77], off offset:192
	global_load_dword v69, v[40:41], off offset:192
	s_waitcnt vmcnt(10)
	v_mul_f32_e64 v39, |v38|, s20
	v_exp_f32_e32 v40, v39
	s_mov_b32 s20, 0x3cf5c28f
	v_cmp_ngt_f32_e32 vcc, s20, v40
	s_and_saveexec_b64 s[20:21], vcc
	v_readlane_b32 s94, v250, 11
	s_xor_b64 s[20:21], exec, s[20:21]
	v_readlane_b32 s95, v250, 12
	v_readlane_b32 s33, v250, 22
	s_movk_i32 s45, 0x1ff
	s_cbranch_execz .LBB0_643
	v_add_f32_e32 v39, 1.0, v40
	s_mov_b32 s30, 0x800000
	v_cmp_gt_f32_e32 vcc, s30, v39
	s_mov_b32 s30, 0x3f317217
	s_nop 0
	v_cndmask_b32_e64 v40, 0, 32, vcc
	v_ldexp_f32 v39, v39, v40
	v_log_f32_e32 v39, v39
	s_nop 0
	v_mul_f32_e32 v40, 0x3f317217, v39
	v_fma_f32 v40, v39, s30, -v40
	v_fmac_f32_e32 v40, 0x3377d1cf, v39
	s_mov_b32 s30, 0x7f800000
	v_fmac_f32_e32 v40, 0x3f317217, v39
	v_cmp_lt_f32_e64 s[40:41], |v39|, s30
	s_nop 1
	v_cndmask_b32_e64 v39, v39, v40, s[40:41]
	v_cndmask_b32_e32 v40, 0, v232, vcc
	v_sub_f32_e32 v39, v39, v40
.LBB0_643:
	s_andn2_saveexec_b64 s[20:21], s[20:21]
	v_fmamk_f32 v39, v40, 0xbe800000, v228
	v_fma_f32 v39, -v40, v39, 0.5
	v_fma_f32 v39, -v40, v39, 1.0
	v_mul_f32_e32 v39, v40, v39
	s_or_b64 exec, exec, s[20:21]
	v_add_f32_e32 v30, v30, v37
	v_mul_f32_e32 v30, 0xbfb8aa3b, v30
	v_exp_f32_e32 v30, v30
	s_mov_b32 s20, 0xbe800000
	v_add_f32_e32 v30, 1.0, v30
	v_rcp_f32_e32 v40, v30
	v_max_f32_e64 v30, -v38, -v38
	v_max_f32_e32 v30, 0, v30
	v_add_f32_e32 v30, v30, v39
	v_mul_f32_e32 v38, 0xc1000000, v40
	v_mul_f32_e32 v39, v38, v30
	v_mul_f32_e32 v38, 0x3fb8aa3b, v39
	v_exp_f32_e32 v38, v38
	v_add_f32_e32 v40, v39, v39
	v_cmp_nlt_f32_e32 vcc, s20, v40
	s_and_saveexec_b64 s[20:21], vcc
	s_xor_b64 s[20:21], exec, s[20:21]
	v_fma_f32 v39, -v38, v38, 1.0
	s_andn2_saveexec_b64 s[20:21], s[20:21]
	v_fmamk_f32 v39, v40, 0x3ab60b61, v229
	v_fmaak_f32 v39, v40, v39, 0x3d2aaaab
	v_fmaak_f32 v39, v40, v39, 0x3e2aaaab
	v_fma_f32 v39, v40, v39, 0.5
	v_fma_f32 v39, v40, v39, 1.0
	v_mul_f32_e64 v39, v39, -v40
	s_or_b64 exec, exec, s[20:21]
	s_waitcnt vmcnt(9)
	v_add_f32_e32 v26, v26, v0
	v_mul_f32_e32 v26, 0xbfb8aa3b, v26
	v_mul_f32_e32 v40, 0x4f800000, v39
	v_cmp_gt_f32_e32 vcc, s26, v39
	v_exp_f32_e32 v26, v26
	v_add_f32_e32 v31, v31, v37
	v_cndmask_b32_e32 v39, v39, v40, vcc
	v_sqrt_f32_e32 v40, v39
	v_add_f32_e32 v26, 1.0, v26
	v_rcp_f32_e32 v41, v26
	v_mul_f32_e32 v31, 0xbfb8aa3b, v31
	v_add_u32_e32 v26, -1, v40
	v_fma_f32 v42, -v26, v40, v39
	v_cmp_ge_f32_e64 s[40:41], 0, v42
	v_add_u32_e32 v42, 1, v40
	v_exp_f32_e32 v31, v31
	v_cndmask_b32_e64 v26, v40, v26, s[40:41]
	v_fma_f32 v40, -v42, v40, v39
	v_cmp_lt_f32_e64 s[40:41], 0, v40
	v_lshrrev_b32_e32 v35, 4, v35
	s_and_b32 s15, s15, -16
	v_cndmask_b32_e64 v26, v26, v42, s[40:41]
	v_mul_f32_e32 v40, 0x37800000, v26
	v_cndmask_b32_e32 v40, v26, v40, vcc
	v_lshlrev_b32_e32 v26, 10, v35
	v_add_f32_e32 v31, 1.0, v31
	v_lshl_or_b32 v26, s15, 8, v26
	v_rcp_f32_e32 v31, v31
	v_or_b32_e32 v35, v26, v36
	v_lshl_add_u32 v35, v35, 2, 0
	ds_read_b32 v42, v35 offset:17920
	v_cmp_class_f32_e32 vcc, v39, v230
	v_mul_f32_e32 v31, 0xc1000000, v31
	s_mov_b32 s15, 0xbe800000
	v_cndmask_b32_e32 v39, v40, v39, vcc
	v_mul_f32_e32 v40, v31, v30
	v_mul_f32_e32 v31, 0x3fb8aa3b, v40
	v_mul_f32_e32 v39, v41, v39
	v_exp_f32_e32 v31, v31
	s_waitcnt lgkmcnt(0)
; __device__ __forceinline__ float sigmoidf_(float x) { return __builtin_amdgcn_rcpf(1.0f + __expf(-x)); }
; __device__ __forceinline__ float softplusf_(float x) { const float e = __expf(-fabsf(x)); const float lg = (e < 0.03f) ? e * (1.0f - e * (0.5f - e * (0.33333334f - 0.25f * e))) : __logf(1.0f + e); return fmaxf(x, 0.f) + lg; }
; __device__ __forceinline__ void mixer_pre_item(int item, const float* const* in, int l, unsigned char* ws, LAS unsigned char* lds, int tid, int lane, int wave) {
;     ...
;         for (int nf = 0; nf < 4; ++nf) {
;             const int ch = 64 * hb + 16 * nf + fr;
;             const float ba = in[11][l * 256 + ch], bx = in[13][l * 256 + ch], sp = softplusf_(-in[14][l * 256 + ch]);
; #pragma unroll
;             for (int jj = 0; jj < 4; ++jj) { const int tok = 16 * mf + 4 * q + jj;
;                 const float r = sigmoidf_(aa[nf][jj] + ba), ig = sigmoidf_(ax[nf][jj] + bx), la = -8.0f * r * sp, a = __expf(la), x2 = 2.0f * la;
;                 const float om = (x2 > -0.25f) ? -x2 * (1.0f + x2 * (0.5f + x2 * (0.16666667f + x2 * (0.041666668f + x2 * (0.008333334f + x2 * 0.0013888889f))))) : 1.0f - a * a;
;                 const float mult = sqrtf(om);
;                 const float xr = XRF[tok * 256 + ch]; AF[tok * 256 + ch] = a; XRF[tok * 256 + ch] = mult * ig * xr; }
	v_mul_f32_e32 v39, v42, v39
	ds_write2st64_b32 v35, v39, v38 offset0:70 offset1:198
	v_add_f32_e32 v38, v40, v40
	v_cmp_nlt_f32_e32 vcc, s15, v38
	s_and_saveexec_b64 s[20:21], vcc
	s_xor_b64 s[20:21], exec, s[20:21]
	v_fma_f32 v35, -v31, v31, 1.0
	s_andn2_saveexec_b64 s[20:21], s[20:21]
	v_fmamk_f32 v35, v38, 0x3ab60b61, v229
	v_fmaak_f32 v35, v38, v35, 0x3d2aaaab
	v_fmaak_f32 v35, v38, v35, 0x3e2aaaab
	v_fma_f32 v35, v38, v35, 0.5
	v_fma_f32 v35, v38, v35, 1.0
	v_mul_f32_e64 v35, v35, -v38
	s_or_b64 exec, exec, s[20:21]
	v_mul_f32_e32 v38, 0x4f800000, v35
	v_cmp_gt_f32_e32 vcc, s26, v35
	v_add_f32_e32 v27, v27, v0
	v_mul_f32_e32 v27, 0xbfb8aa3b, v27
	v_cndmask_b32_e32 v35, v35, v38, vcc
	v_sqrt_f32_e32 v38, v35
	v_add_f32_e32 v32, v32, v37
	v_exp_f32_e32 v27, v27
	v_mul_f32_e32 v32, 0xbfb8aa3b, v32
	v_add_u32_e32 v39, -1, v38
	v_fma_f32 v40, -v39, v38, v35
	v_cmp_ge_f32_e64 s[40:41], 0, v40
	v_add_u32_e32 v40, 1, v38
	v_add_u32_e32 v26, v26, v36
	v_cndmask_b32_e64 v39, v38, v39, s[40:41]
	v_fma_f32 v38, -v40, v38, v35
	v_cmp_lt_f32_e64 s[40:41], 0, v38
	v_add_f32_e32 v27, 1.0, v27
	v_rcp_f32_e32 v27, v27
	v_cndmask_b32_e64 v38, v39, v40, s[40:41]
	v_mul_f32_e32 v39, 0x37800000, v38
	v_cndmask_b32_e32 v38, v38, v39, vcc
	v_exp_f32_e32 v39, v32
	v_lshl_add_u32 v32, v26, 2, 0
	ds_read_b32 v26, v32 offset:18944
	v_cmp_class_f32_e32 vcc, v35, v230
	v_add_f32_e32 v39, 1.0, v39
	v_rcp_f32_e32 v39, v39
	v_cndmask_b32_e32 v35, v38, v35, vcc
	v_mul_f32_e32 v27, v27, v35
	s_waitcnt lgkmcnt(0)
	v_mul_f32_e32 v27, v26, v27
	v_mul_f32_e32 v26, 0xc1000000, v39
	v_mul_f32_e32 v35, v26, v30
	v_mul_f32_e32 v26, 0x3fb8aa3b, v35
	v_exp_f32_e32 v26, v26
	ds_write2st64_b32 v32, v27, v31 offset0:74 offset1:202
	v_add_f32_e32 v31, v35, v35
	v_cmp_nlt_f32_e32 vcc, s15, v31
	s_and_saveexec_b64 s[20:21], vcc
	s_xor_b64 s[20:21], exec, s[20:21]
	v_fma_f32 v27, -v26, v26, 1.0
	s_andn2_saveexec_b64 s[20:21], s[20:21]
	v_fmamk_f32 v27, v31, 0x3ab60b61, v229
	v_fmaak_f32 v27, v31, v27, 0x3d2aaaab
	v_fmaak_f32 v27, v31, v27, 0x3e2aaaab
	v_fma_f32 v27, v31, v27, 0.5
	v_fma_f32 v27, v31, v27, 1.0
	v_mul_f32_e64 v27, v27, -v31
	s_or_b64 exec, exec, s[20:21]
	v_mul_f32_e32 v31, 0x4f800000, v27
	v_cmp_gt_f32_e32 vcc, s26, v27
	v_add_f32_e32 v28, v28, v0
	v_mul_f32_e32 v28, 0xbfb8aa3b, v28
	v_cndmask_b32_e32 v27, v27, v31, vcc
	v_sqrt_f32_e32 v31, v27
	v_add_f32_e32 v33, v33, v37
	v_exp_f32_e32 v28, v28
	v_mul_f32_e32 v33, 0xbfb8aa3b, v33
	v_add_u32_e32 v35, -1, v31
	v_fma_f32 v38, -v35, v31, v27
	v_cmp_ge_f32_e64 s[40:41], 0, v38
	v_add_u32_e32 v38, 1, v31
	v_exp_f32_e32 v33, v33
	v_cndmask_b32_e64 v35, v31, v35, s[40:41]
	v_fma_f32 v31, -v38, v31, v27
	v_cmp_lt_f32_e64 s[40:41], 0, v31
	v_add_f32_e32 v28, 1.0, v28
	v_rcp_f32_e32 v28, v28
	v_cndmask_b32_e64 v31, v35, v38, s[40:41]
	v_mul_f32_e32 v35, 0x37800000, v31
	v_cndmask_b32_e32 v31, v31, v35, vcc
	ds_read_b32 v35, v32 offset:19968
	v_add_f32_e32 v33, 1.0, v33
	v_rcp_f32_e32 v33, v33
	v_cmp_class_f32_e32 vcc, v27, v230
	s_nop 1
	v_cndmask_b32_e32 v27, v31, v27, vcc
	v_mul_f32_e32 v27, v28, v27
	s_waitcnt lgkmcnt(0)
	v_mul_f32_e32 v28, v35, v27
	v_mul_f32_e32 v27, 0xc1000000, v33
	v_mul_f32_e32 v30, v27, v30
	v_mul_f32_e32 v27, 0x3fb8aa3b, v30
	v_exp_f32_e32 v27, v27
	ds_write2st64_b32 v32, v28, v26 offset0:78 offset1:206
	v_add_f32_e32 v28, v30, v30
	v_cmp_nlt_f32_e32 vcc, s15, v28
	s_and_saveexec_b64 s[20:21], vcc
	s_xor_b64 s[20:21], exec, s[20:21]
	v_fma_f32 v26, -v27, v27, 1.0
	s_andn2_saveexec_b64 s[20:21], s[20:21]
	v_fmamk_f32 v26, v28, 0x3ab60b61, v229
	v_fmaak_f32 v26, v28, v26, 0x3d2aaaab
	v_fmaak_f32 v26, v28, v26, 0x3e2aaaab
	v_fma_f32 v26, v28, v26, 0.5
	v_fma_f32 v26, v28, v26, 1.0
	v_mul_f32_e64 v26, v26, -v28
	s_or_b64 exec, exec, s[20:21]
	v_cmp_gt_f32_e32 vcc, s26, v26
	v_mul_f32_e32 v28, 0x4f800000, v26
	v_add_f32_e32 v0, v29, v0
	v_cndmask_b32_e32 v26, v26, v28, vcc
	v_sqrt_f32_e32 v28, v26
	v_mul_f32_e32 v0, 0xbfb8aa3b, v0
	v_exp_f32_e32 v0, v0
	v_readlane_b32 s20, v248, 51
	v_add_u32_e32 v29, -1, v28
	v_fma_f32 v30, -v29, v28, v26
	v_cmp_ge_f32_e64 s[40:41], 0, v30
	v_add_u32_e32 v30, 1, v28
	v_add_f32_e32 v0, 1.0, v0
	v_cndmask_b32_e64 v29, v28, v29, s[40:41]
	v_fma_f32 v28, -v30, v28, v26
	v_cmp_lt_f32_e64 s[40:41], 0, v28
	v_rcp_f32_e32 v0, v0
	v_readlane_b32 s48, v248, 55
	v_cndmask_b32_e64 v28, v29, v30, s[40:41]
	v_mul_f32_e32 v29, 0x37800000, v28
	v_cndmask_b32_e32 v28, v28, v29, vcc
	v_cmp_class_f32_e32 vcc, v26, v230
	v_readlane_b32 s21, v248, 52
	v_readlane_b32 s49, v248, 56
	v_cndmask_b32_e32 v26, v28, v26, vcc
	ds_read_b32 v28, v32 offset:20992
	v_mul_f32_e32 v0, v0, v26
	v_readlane_b32 s50, v248, 57
	v_readlane_b32 s51, v248, 58
	s_mov_b32 s15, 0xbfb8aa3b
	s_waitcnt lgkmcnt(0)
	v_mul_f32_e32 v0, v28, v0
	ds_write2st64_b32 v32, v0, v27 offset0:82 offset1:210
	v_add_u32_e32 v0, s1, v36
	v_lshlrev_b64 v[26:27], 2, v[0:1]
	v_lshl_add_u64 v[28:29], s[20:21], 0, v[26:27]
	v_lshl_add_u64 v[30:31], s[48:49], 0, v[26:27]
	v_lshl_add_u64 v[26:27], s[50:51], 0, v[26:27]
	s_waitcnt vmcnt(0)
	v_mov_b32_e32 v35, v70
	v_mov_b32_e32 v33, v64
	v_mov_b32_e32 v0, v67
	v_readlane_b32 s52, v248, 59
	v_readlane_b32 s53, v248, 60
	v_readlane_b32 s54, v248, 61
	v_readlane_b32 s55, v248, 62
	v_readlane_b32 s56, v248, 63
	v_readlane_b32 s57, v250, 0
	v_readlane_b32 s58, v250, 1
	v_readlane_b32 s59, v250, 2
	v_readlane_b32 s60, v250, 3
	v_readlane_b32 s61, v250, 4
	v_readlane_b32 s62, v250, 5
	v_readlane_b32 s63, v250, 6
	s_waitcnt vmcnt(2)
	v_mul_f32_e64 v36, |v35|, s15
	v_exp_f32_e32 v36, v36
	s_mov_b32 s15, 0x3cf5c28f
	v_cmp_ngt_f32_e32 vcc, s15, v36
	s_and_saveexec_b64 s[20:21], vcc
	s_xor_b64 s[20:21], exec, s[20:21]
	s_cbranch_execz .LBB0_663
	v_add_f32_e32 v36, 1.0, v36
	s_mov_b32 s15, 0x800000
	v_cmp_gt_f32_e32 vcc, s15, v36
	s_mov_b32 s15, 0x3f317217
	s_nop 0
	v_cndmask_b32_e64 v37, 0, 32, vcc
	v_ldexp_f32 v36, v36, v37
	v_log_f32_e32 v36, v36
	s_nop 0
	v_mul_f32_e32 v37, 0x3f317217, v36
	v_fma_f32 v37, v36, s15, -v37
	v_fmac_f32_e32 v37, 0x3377d1cf, v36
	s_mov_b32 s15, 0x7f800000
	v_fmac_f32_e32 v37, 0x3f317217, v36
	v_cmp_lt_f32_e64 s[40:41], |v36|, s15
	s_nop 1
	v_cndmask_b32_e64 v36, v36, v37, s[40:41]
	v_cndmask_b32_e32 v37, 0, v232, vcc
	v_sub_f32_e32 v37, v36, v37
; __device__ __forceinline__ float sigmoidf_(float x) { return __builtin_amdgcn_rcpf(1.0f + __expf(-x)); }
; __device__ __forceinline__ void mixer_pre_item(int item, const float* const* in, int l, unsigned char* ws, LAS unsigned char* lds, int tid, int lane, int wave) {
;     ...
;             for (int jj = 0; jj < 4; ++jj) { const int tok = 16 * mf + 4 * q + jj;
;                 const float r = sigmoidf_(aa[nf][jj] + ba), ig = sigmoidf_(ax[nf][jj] + bx), la = -8.0f * r * sp, a = __expf(la), x2 = 2.0f * la;
;                 const float om = (x2 > -0.25f) ? -x2 * (1.0f + x2 * (0.5f + x2 * (0.16666667f + x2 * (0.041666668f + x2 * (0.008333334f + x2 * 0.0013888889f))))) : 1.0f - a * a;
;                 const float mult = sqrtf(om);
;                 const float xr = XRF[tok * 256 + ch]; AF[tok * 256 + ch] = a; XRF[tok * 256 + ch] = mult * ig * xr; }
.LBB0_663:
	s_andn2_saveexec_b64 s[20:21], s[20:21]
	v_fmamk_f32 v37, v36, 0xbe800000, v228
	v_fma_f32 v37, -v36, v37, 0.5
	v_fma_f32 v37, -v36, v37, 1.0
	v_mul_f32_e32 v37, v36, v37
	s_or_b64 exec, exec, s[20:21]
	s_waitcnt vmcnt(1)
	v_add_f32_e32 v22, v22, v33
	v_mul_f32_e32 v22, 0xbfb8aa3b, v22
	v_exp_f32_e32 v22, v22
	s_mov_b32 s15, 0xbe800000
	v_add_f32_e32 v22, 1.0, v22
	v_rcp_f32_e32 v36, v22
	v_max_f32_e64 v22, -v35, -v35
	v_max_f32_e32 v22, 0, v22
	v_add_f32_e32 v22, v22, v37
	v_mul_f32_e32 v35, 0xc1000000, v36
	v_mul_f32_e32 v36, v35, v22
	v_mul_f32_e32 v35, 0x3fb8aa3b, v36
	v_exp_f32_e32 v35, v35
	v_add_f32_e32 v37, v36, v36
	v_cmp_nlt_f32_e32 vcc, s15, v37
	s_and_saveexec_b64 s[20:21], vcc
	s_xor_b64 s[20:21], exec, s[20:21]
	v_fma_f32 v36, -v35, v35, 1.0
	s_andn2_saveexec_b64 s[20:21], s[20:21]
	v_fmamk_f32 v36, v37, 0x3ab60b61, v229
	v_fmaak_f32 v36, v37, v36, 0x3d2aaaab
	v_fmaak_f32 v36, v37, v36, 0x3e2aaaab
	v_fma_f32 v36, v37, v36, 0.5
	v_fma_f32 v36, v37, v36, 1.0
	v_mul_f32_e64 v36, v36, -v37
	s_or_b64 exec, exec, s[20:21]
	v_mul_f32_e32 v37, 0x4f800000, v36
	v_cmp_gt_f32_e32 vcc, s26, v36
	v_add_f32_e32 v23, v23, v33
	v_mul_f32_e32 v23, 0xbfb8aa3b, v23
	v_cndmask_b32_e32 v36, v36, v37, vcc
	v_sqrt_f32_e32 v37, v36
	v_exp_f32_e32 v23, v23
	s_waitcnt vmcnt(0)
	v_add_f32_e32 v18, v18, v0
	v_mul_f32_e32 v18, 0xbfb8aa3b, v18
	v_add_u32_e32 v38, -1, v37
	v_fma_f32 v39, -v38, v37, v36
	v_exp_f32_e32 v18, v18
	v_cmp_ge_f32_e64 s[40:41], 0, v39
	v_add_u32_e32 v39, 1, v37
	v_add_f32_e32 v23, 1.0, v23
	v_cndmask_b32_e64 v38, v37, v38, s[40:41]
	v_fma_f32 v37, -v39, v37, v36
	v_cmp_lt_f32_e64 s[40:41], 0, v37
	v_rcp_f32_e32 v23, v23
	v_add_f32_e32 v18, 1.0, v18
	v_cndmask_b32_e64 v37, v38, v39, s[40:41]
	v_mul_f32_e32 v38, 0x37800000, v37
	v_rcp_f32_e32 v18, v18
	v_cndmask_b32_e32 v37, v37, v38, vcc
	ds_read_b32 v38, v32 offset:17984
	v_cmp_class_f32_e32 vcc, v36, v230
	v_mul_f32_e32 v23, 0xc1000000, v23
	s_nop 0
	v_cndmask_b32_e32 v36, v37, v36, vcc
	v_mul_f32_e32 v37, v23, v22
	v_mul_f32_e32 v23, 0x3fb8aa3b, v37
	v_mul_f32_e32 v18, v18, v36
	v_exp_f32_e32 v23, v23
	s_waitcnt lgkmcnt(0)
	v_mul_f32_e32 v36, v38, v18
	v_add_u32_e32 v18, 64, v32
	ds_write2st64_b32 v18, v36, v35 offset0:70 offset1:198
	v_add_f32_e32 v36, v37, v37
	v_cmp_nlt_f32_e32 vcc, s15, v36
	s_and_saveexec_b64 s[20:21], vcc
	s_xor_b64 s[20:21], exec, s[20:21]
	v_fma_f32 v35, -v23, v23, 1.0
	s_andn2_saveexec_b64 s[20:21], s[20:21]
	v_fmamk_f32 v35, v36, 0x3ab60b61, v229
	v_fmaak_f32 v35, v36, v35, 0x3d2aaaab
	v_fmaak_f32 v35, v36, v35, 0x3e2aaaab
	v_fma_f32 v35, v36, v35, 0.5
	v_fma_f32 v35, v36, v35, 1.0
	v_mul_f32_e64 v35, v35, -v36
	s_or_b64 exec, exec, s[20:21]
	v_mul_f32_e32 v36, 0x4f800000, v35
	v_cmp_gt_f32_e32 vcc, s26, v35
	v_add_f32_e32 v19, v19, v0
	v_mul_f32_e32 v19, 0xbfb8aa3b, v19
	v_cndmask_b32_e32 v35, v35, v36, vcc
	v_sqrt_f32_e32 v36, v35
	v_add_f32_e32 v24, v24, v33
	v_exp_f32_e32 v19, v19
	v_mul_f32_e32 v24, 0xbfb8aa3b, v24
	v_add_u32_e32 v37, -1, v36
	v_fma_f32 v38, -v37, v36, v35
	v_cmp_ge_f32_e64 s[40:41], 0, v38
	v_add_u32_e32 v38, 1, v36
	v_exp_f32_e32 v24, v24
	v_cndmask_b32_e64 v37, v36, v37, s[40:41]
	v_fma_f32 v36, -v38, v36, v35
	v_cmp_lt_f32_e64 s[40:41], 0, v36
	v_add_f32_e32 v19, 1.0, v19
	v_rcp_f32_e32 v19, v19
	v_cndmask_b32_e64 v36, v37, v38, s[40:41]
	v_mul_f32_e32 v37, 0x37800000, v36
	v_cndmask_b32_e32 v36, v36, v37, vcc
	ds_read_b32 v37, v32 offset:19008
	v_add_f32_e32 v24, 1.0, v24
	v_rcp_f32_e32 v24, v24
	v_cmp_class_f32_e32 vcc, v35, v230
	s_nop 1
	v_cndmask_b32_e32 v35, v36, v35, vcc
	v_mul_f32_e32 v19, v19, v35
	s_waitcnt lgkmcnt(0)
	v_mul_f32_e32 v35, v37, v19
	v_mul_f32_e32 v19, 0xc1000000, v24
	v_mul_f32_e32 v24, v19, v22
	v_mul_f32_e32 v19, 0x3fb8aa3b, v24
	v_exp_f32_e32 v19, v19
	ds_write2st64_b32 v18, v35, v23 offset0:74 offset1:202
	v_add_f32_e32 v23, v24, v24
	v_cmp_nlt_f32_e32 vcc, s15, v23
	s_and_saveexec_b64 s[20:21], vcc
	s_xor_b64 s[20:21], exec, s[20:21]
	v_fma_f32 v18, -v19, v19, 1.0
	s_andn2_saveexec_b64 s[20:21], s[20:21]
	v_fmamk_f32 v18, v23, 0x3ab60b61, v229
	v_fmaak_f32 v18, v23, v18, 0x3d2aaaab
	v_fmaak_f32 v18, v23, v18, 0x3e2aaaab
	v_fma_f32 v18, v23, v18, 0.5
	v_fma_f32 v18, v23, v18, 1.0
	v_mul_f32_e64 v18, v18, -v23
	s_or_b64 exec, exec, s[20:21]
	v_mul_f32_e32 v23, 0x4f800000, v18
	v_cmp_gt_f32_e32 vcc, s26, v18
	v_add_f32_e32 v20, v20, v0
	v_mul_f32_e32 v20, 0xbfb8aa3b, v20
	v_cndmask_b32_e32 v23, v18, v23, vcc
	v_sqrt_f32_e32 v24, v23
	v_add_f32_e32 v25, v25, v33
	v_exp_f32_e32 v20, v20
	v_mul_f32_e32 v25, 0xbfb8aa3b, v25
	v_add_u32_e32 v35, -1, v24
	v_fma_f32 v36, -v35, v24, v23
	v_cmp_ge_f32_e64 s[40:41], 0, v36
	v_add_u32_e32 v36, 1, v24
	v_exp_f32_e32 v25, v25
	v_cndmask_b32_e64 v35, v24, v35, s[40:41]
	v_fma_f32 v24, -v36, v24, v23
	v_cmp_lt_f32_e64 s[40:41], 0, v24
	v_add_u32_e32 v18, 64, v32
	v_add_f32_e32 v20, 1.0, v20
	v_cndmask_b32_e64 v24, v35, v36, s[40:41]
	v_mul_f32_e32 v33, 0x37800000, v24
	v_rcp_f32_e32 v20, v20
	v_cndmask_b32_e32 v24, v24, v33, vcc
	ds_read_b32 v33, v18 offset:19968
	v_add_f32_e32 v25, 1.0, v25
	v_rcp_f32_e32 v25, v25
	v_cmp_class_f32_e32 vcc, v23, v230
	s_nop 1
	v_cndmask_b32_e32 v23, v24, v23, vcc
	v_mul_f32_e32 v20, v20, v23
	s_waitcnt lgkmcnt(0)
; __device__ __forceinline__ float sigmoidf_(float x) { return __builtin_amdgcn_rcpf(1.0f + __expf(-x)); }
; __device__ __forceinline__ float softplusf_(float x) { const float e = __expf(-fabsf(x)); const float lg = (e < 0.03f) ? e * (1.0f - e * (0.5f - e * (0.33333334f - 0.25f * e))) : __logf(1.0f + e); return fmaxf(x, 0.f) + lg; }
; __device__ __forceinline__ void mixer_pre_item(int item, const float* const* in, int l, unsigned char* ws, LAS unsigned char* lds, int tid, int lane, int wave) {
;     ...
;             const float ba = in[11][l * 256 + ch], bx = in[13][l * 256 + ch], sp = softplusf_(-in[14][l * 256 + ch]);
; #pragma unroll
;             for (int jj = 0; jj < 4; ++jj) { const int tok = 16 * mf + 4 * q + jj;
;                 const float r = sigmoidf_(aa[nf][jj] + ba), ig = sigmoidf_(ax[nf][jj] + bx), la = -8.0f * r * sp, a = __expf(la), x2 = 2.0f * la;
;                 const float om = (x2 > -0.25f) ? -x2 * (1.0f + x2 * (0.5f + x2 * (0.16666667f + x2 * (0.041666668f + x2 * (0.008333334f + x2 * 0.0013888889f))))) : 1.0f - a * a;
;                 const float mult = sqrtf(om);
;                 const float xr = XRF[tok * 256 + ch]; AF[tok * 256 + ch] = a; XRF[tok * 256 + ch] = mult * ig * xr; }
	v_mul_f32_e32 v23, v33, v20
	v_mul_f32_e32 v20, 0xc1000000, v25
	v_mul_f32_e32 v22, v20, v22
	v_mul_f32_e32 v20, 0x3fb8aa3b, v22
	v_exp_f32_e32 v20, v20
	v_add_f32_e32 v22, v22, v22
	v_cmp_nlt_f32_e32 vcc, s15, v22
	ds_write2st64_b32 v18, v23, v19 offset0:78 offset1:206
	s_and_saveexec_b64 s[20:21], vcc
	s_xor_b64 s[20:21], exec, s[20:21]
	v_fma_f32 v19, -v20, v20, 1.0
	s_andn2_saveexec_b64 s[20:21], s[20:21]
	v_fmamk_f32 v19, v22, 0x3ab60b61, v229
	v_fmaak_f32 v19, v22, v19, 0x3d2aaaab
	v_fmaak_f32 v19, v22, v19, 0x3e2aaaab
	v_fma_f32 v19, v22, v19, 0.5
	v_fma_f32 v19, v22, v19, 1.0
	v_mul_f32_e64 v19, v19, -v22
	s_or_b64 exec, exec, s[20:21]
	v_add_f32_e32 v0, v21, v0
	v_cmp_gt_f32_e32 vcc, s26, v19
	v_mul_f32_e32 v21, 0x4f800000, v19
	v_mul_f32_e32 v0, 0xbfb8aa3b, v0
	v_cndmask_b32_e32 v19, v19, v21, vcc
	v_sqrt_f32_e32 v21, v19
	v_exp_f32_e32 v0, v0
	s_mov_b32 s15, 0xbfb8aa3b
	v_add_u32_e32 v22, -1, v21
	v_fma_f32 v23, -v22, v21, v19
	v_cmp_ge_f32_e64 s[40:41], 0, v23
	v_add_u32_e32 v23, 1, v21
	v_add_f32_e32 v0, 1.0, v0
	v_cndmask_b32_e64 v22, v21, v22, s[40:41]
	v_fma_f32 v21, -v23, v21, v19
	v_cmp_lt_f32_e64 s[40:41], 0, v21
	v_rcp_f32_e32 v0, v0
	s_nop 0
	v_cndmask_b32_e64 v21, v22, v23, s[40:41]
	v_mul_f32_e32 v22, 0x37800000, v21
	v_cndmask_b32_e32 v21, v21, v22, vcc
	v_cmp_class_f32_e32 vcc, v19, v230
	s_nop 1
	v_cndmask_b32_e32 v19, v21, v19, vcc
	ds_read_b32 v21, v18 offset:20992
	v_mul_f32_e32 v0, v0, v19
	s_waitcnt lgkmcnt(0)
	v_mul_f32_e32 v0, v21, v0
	ds_write2st64_b32 v18, v0, v20 offset0:82 offset1:210
	v_mov_b32_e32 v18, v65
	v_mov_b32_e32 v0, v68
	v_mov_b32_e32 v19, v71
	s_waitcnt vmcnt(0)
	v_mul_f32_e64 v20, |v19|, s15
	v_exp_f32_e32 v20, v20
	s_mov_b32 s15, 0x3cf5c28f
	v_cmp_ngt_f32_e32 vcc, s15, v20
	s_and_saveexec_b64 s[20:21], vcc
	s_xor_b64 s[20:21], exec, s[20:21]
	s_cbranch_execz .LBB0_683
	v_add_f32_e32 v20, 1.0, v20
	s_mov_b32 s15, 0x800000
	v_cmp_gt_f32_e32 vcc, s15, v20
	s_mov_b32 s15, 0x3f317217
	s_nop 0
	v_cndmask_b32_e64 v21, 0, 32, vcc
	v_ldexp_f32 v20, v20, v21
	v_log_f32_e32 v20, v20
	s_nop 0
	v_mul_f32_e32 v21, 0x3f317217, v20
	v_fma_f32 v21, v20, s15, -v21
	v_fmac_f32_e32 v21, 0x3377d1cf, v20
	s_mov_b32 s15, 0x7f800000
	v_fmac_f32_e32 v21, 0x3f317217, v20
	v_cmp_lt_f32_e64 s[40:41], |v20|, s15
	s_nop 1
	v_cndmask_b32_e64 v20, v20, v21, s[40:41]
	v_cndmask_b32_e32 v21, 0, v232, vcc
	v_sub_f32_e32 v21, v20, v21
.LBB0_683:
	s_andn2_saveexec_b64 s[20:21], s[20:21]
	v_fmamk_f32 v21, v20, 0xbe800000, v228
	v_fma_f32 v21, -v20, v21, 0.5
	v_fma_f32 v21, -v20, v21, 1.0
	v_mul_f32_e32 v21, v20, v21
	s_or_b64 exec, exec, s[20:21]
	v_add_f32_e32 v14, v14, v18
	v_mul_f32_e32 v14, 0xbfb8aa3b, v14
	v_exp_f32_e32 v14, v14
	s_mov_b32 s15, 0xbe800000
	v_add_f32_e32 v14, 1.0, v14
	v_rcp_f32_e32 v20, v14
	v_max_f32_e64 v14, -v19, -v19
	v_max_f32_e32 v14, 0, v14
	v_add_f32_e32 v14, v14, v21
	v_mul_f32_e32 v19, 0xc1000000, v20
	v_mul_f32_e32 v20, v19, v14
	v_mul_f32_e32 v19, 0x3fb8aa3b, v20
	v_exp_f32_e32 v19, v19
	v_add_f32_e32 v21, v20, v20
	v_cmp_nlt_f32_e32 vcc, s15, v21
	s_and_saveexec_b64 s[20:21], vcc
	s_xor_b64 s[20:21], exec, s[20:21]
	v_fma_f32 v20, -v19, v19, 1.0
	s_andn2_saveexec_b64 s[20:21], s[20:21]
	v_fmamk_f32 v20, v21, 0x3ab60b61, v229
	v_fmaak_f32 v20, v21, v20, 0x3d2aaaab
	v_fmaak_f32 v20, v21, v20, 0x3e2aaaab
	v_fma_f32 v20, v21, v20, 0.5
	v_fma_f32 v20, v21, v20, 1.0
	v_mul_f32_e64 v20, v20, -v21
	s_or_b64 exec, exec, s[20:21]
	v_mul_f32_e32 v21, 0x4f800000, v20
	v_cmp_gt_f32_e32 vcc, s26, v20
	v_add_f32_e32 v15, v15, v18
	v_mul_f32_e32 v15, 0xbfb8aa3b, v15
	v_cndmask_b32_e32 v20, v20, v21, vcc
	v_sqrt_f32_e32 v21, v20
	v_exp_f32_e32 v15, v15
	v_add_f32_e32 v10, v10, v0
	v_mul_f32_e32 v10, 0xbfb8aa3b, v10
	v_add_u32_e32 v22, -1, v21
	v_fma_f32 v23, -v22, v21, v20
	v_exp_f32_e32 v10, v10
	v_cmp_ge_f32_e64 s[40:41], 0, v23
	v_add_u32_e32 v23, 1, v21
	v_add_f32_e32 v15, 1.0, v15
	v_cndmask_b32_e64 v22, v21, v22, s[40:41]
	v_fma_f32 v21, -v23, v21, v20
	v_cmp_lt_f32_e64 s[40:41], 0, v21
	v_rcp_f32_e32 v15, v15
	v_add_f32_e32 v10, 1.0, v10
	v_cndmask_b32_e64 v21, v22, v23, s[40:41]
	v_mul_f32_e32 v22, 0x37800000, v21
	v_rcp_f32_e32 v10, v10
	v_cndmask_b32_e32 v21, v21, v22, vcc
	ds_read_b32 v22, v32 offset:18048
	v_cmp_class_f32_e32 vcc, v20, v230
	v_mul_f32_e32 v15, 0xc1000000, v15
	s_nop 0
	v_cndmask_b32_e32 v20, v21, v20, vcc
	v_mul_f32_e32 v21, v15, v14
	v_mul_f32_e32 v15, 0x3fb8aa3b, v21
	v_mul_f32_e32 v10, v10, v20
	v_exp_f32_e32 v15, v15
	s_waitcnt lgkmcnt(0)
; __device__ __forceinline__ float sigmoidf_(float x) { return __builtin_amdgcn_rcpf(1.0f + __expf(-x)); }
; __device__ __forceinline__ float softplusf_(float x) { const float e = __expf(-fabsf(x)); const float lg = (e < 0.03f) ? e * (1.0f - e * (0.5f - e * (0.33333334f - 0.25f * e))) : __logf(1.0f + e); return fmaxf(x, 0.f) + lg; }
; __device__ __forceinline__ void mixer_pre_item(int item, const float* const* in, int l, unsigned char* ws, LAS unsigned char* lds, int tid, int lane, int wave) {
;     ...
;             const float ba = in[11][l * 256 + ch], bx = in[13][l * 256 + ch], sp = softplusf_(-in[14][l * 256 + ch]);
; #pragma unroll
;             for (int jj = 0; jj < 4; ++jj) { const int tok = 16 * mf + 4 * q + jj;
;                 const float r = sigmoidf_(aa[nf][jj] + ba), ig = sigmoidf_(ax[nf][jj] + bx), la = -8.0f * r * sp, a = __expf(la), x2 = 2.0f * la;
;                 const float om = (x2 > -0.25f) ? -x2 * (1.0f + x2 * (0.5f + x2 * (0.16666667f + x2 * (0.041666668f + x2 * (0.008333334f + x2 * 0.0013888889f))))) : 1.0f - a * a;
;                 const float mult = sqrtf(om);
;                 const float xr = XRF[tok * 256 + ch]; AF[tok * 256 + ch] = a; XRF[tok * 256 + ch] = mult * ig * xr; }
	v_mul_f32_e32 v20, v22, v10
	v_add_u32_e32 v10, 0x80, v32
	ds_write2st64_b32 v10, v20, v19 offset0:70 offset1:198
	v_add_f32_e32 v20, v21, v21
	v_cmp_nlt_f32_e32 vcc, s15, v20
	s_and_saveexec_b64 s[20:21], vcc
	s_xor_b64 s[20:21], exec, s[20:21]
	v_fma_f32 v19, -v15, v15, 1.0
	s_andn2_saveexec_b64 s[20:21], s[20:21]
	v_fmamk_f32 v19, v20, 0x3ab60b61, v229
	v_fmaak_f32 v19, v20, v19, 0x3d2aaaab
	v_fmaak_f32 v19, v20, v19, 0x3e2aaaab
	v_fma_f32 v19, v20, v19, 0.5
	v_fma_f32 v19, v20, v19, 1.0
	v_mul_f32_e64 v19, v19, -v20
	s_or_b64 exec, exec, s[20:21]
	v_mul_f32_e32 v20, 0x4f800000, v19
	v_cmp_gt_f32_e32 vcc, s26, v19
	v_add_f32_e32 v11, v11, v0
	v_mul_f32_e32 v11, 0xbfb8aa3b, v11
	v_cndmask_b32_e32 v19, v19, v20, vcc
	v_sqrt_f32_e32 v20, v19
	v_add_f32_e32 v16, v16, v18
	v_exp_f32_e32 v11, v11
	v_mul_f32_e32 v16, 0xbfb8aa3b, v16
	v_add_u32_e32 v21, -1, v20
	v_fma_f32 v22, -v21, v20, v19
	v_cmp_ge_f32_e64 s[40:41], 0, v22
	v_add_u32_e32 v22, 1, v20
	v_exp_f32_e32 v16, v16
	v_cndmask_b32_e64 v21, v20, v21, s[40:41]
	v_fma_f32 v20, -v22, v20, v19
	v_cmp_lt_f32_e64 s[40:41], 0, v20
	v_add_f32_e32 v11, 1.0, v11
	v_rcp_f32_e32 v11, v11
	v_cndmask_b32_e64 v20, v21, v22, s[40:41]
	v_mul_f32_e32 v21, 0x37800000, v20
	v_cndmask_b32_e32 v20, v20, v21, vcc
	ds_read_b32 v21, v32 offset:19072
	v_add_f32_e32 v16, 1.0, v16
	v_rcp_f32_e32 v16, v16
	v_cmp_class_f32_e32 vcc, v19, v230
	s_nop 1
	v_cndmask_b32_e32 v19, v20, v19, vcc
	v_mul_f32_e32 v11, v11, v19
	s_waitcnt lgkmcnt(0)
	v_mul_f32_e32 v19, v21, v11
	v_mul_f32_e32 v11, 0xc1000000, v16
	v_mul_f32_e32 v16, v11, v14
	v_mul_f32_e32 v11, 0x3fb8aa3b, v16
	v_exp_f32_e32 v11, v11
	v_add_f32_e32 v16, v16, v16
	v_cmp_nlt_f32_e32 vcc, s15, v16
	ds_write2st64_b32 v10, v19, v15 offset0:74 offset1:202
	s_and_saveexec_b64 s[20:21], vcc
	s_xor_b64 s[20:21], exec, s[20:21]
	v_fma_f32 v15, -v11, v11, 1.0
	s_andn2_saveexec_b64 s[20:21], s[20:21]
	v_fmamk_f32 v15, v16, 0x3ab60b61, v229
	v_fmaak_f32 v15, v16, v15, 0x3d2aaaab
	v_fmaak_f32 v15, v16, v15, 0x3e2aaaab
	v_fma_f32 v15, v16, v15, 0.5
	v_fma_f32 v15, v16, v15, 1.0
	v_mul_f32_e64 v15, v15, -v16
	s_or_b64 exec, exec, s[20:21]
	v_mul_f32_e32 v16, 0x4f800000, v15
	v_cmp_gt_f32_e32 vcc, s26, v15
	v_add_f32_e32 v12, v12, v0
	v_mul_f32_e32 v12, 0xbfb8aa3b, v12
	v_cndmask_b32_e32 v15, v15, v16, vcc
	v_sqrt_f32_e32 v16, v15
	v_add_f32_e32 v17, v17, v18
	v_exp_f32_e32 v12, v12
	v_mul_f32_e32 v17, 0xbfb8aa3b, v17
	v_add_u32_e32 v19, -1, v16
	v_fma_f32 v20, -v19, v16, v15
	v_cmp_ge_f32_e64 s[40:41], 0, v20
	v_add_u32_e32 v20, 1, v16
	v_exp_f32_e32 v17, v17
	v_cndmask_b32_e64 v19, v16, v19, s[40:41]
	v_fma_f32 v16, -v20, v16, v15
	v_cmp_lt_f32_e64 s[40:41], 0, v16
	v_add_f32_e32 v12, 1.0, v12
	v_rcp_f32_e32 v12, v12
	v_cndmask_b32_e64 v16, v19, v20, s[40:41]
	v_mul_f32_e32 v18, 0x37800000, v16
	v_cndmask_b32_e32 v16, v16, v18, vcc
	ds_read_b32 v18, v10 offset:19968
	v_add_f32_e32 v17, 1.0, v17
	v_rcp_f32_e32 v17, v17
	v_cmp_class_f32_e32 vcc, v15, v230
	s_nop 1
	v_cndmask_b32_e32 v15, v16, v15, vcc
	v_mul_f32_e32 v12, v12, v15
	s_waitcnt lgkmcnt(0)
	v_mul_f32_e32 v15, v18, v12
	v_mul_f32_e32 v12, 0xc1000000, v17
	v_mul_f32_e32 v14, v12, v14
	v_mul_f32_e32 v12, 0x3fb8aa3b, v14
	v_exp_f32_e32 v12, v12
	v_add_f32_e32 v14, v14, v14
	v_cmp_nlt_f32_e32 vcc, s15, v14
	ds_write2st64_b32 v10, v15, v11 offset0:78 offset1:206
	s_and_saveexec_b64 s[20:21], vcc
	s_xor_b64 s[20:21], exec, s[20:21]
	v_fma_f32 v11, -v12, v12, 1.0
	s_andn2_saveexec_b64 s[20:21], s[20:21]
	v_fmamk_f32 v11, v14, 0x3ab60b61, v229
	v_fmaak_f32 v11, v14, v11, 0x3d2aaaab
	v_fmaak_f32 v11, v14, v11, 0x3e2aaaab
	v_fma_f32 v11, v14, v11, 0.5
	v_fma_f32 v11, v14, v11, 1.0
	v_mul_f32_e64 v11, v11, -v14
	s_or_b64 exec, exec, s[20:21]
	v_add_f32_e32 v0, v13, v0
	v_cmp_gt_f32_e32 vcc, s26, v11
	v_mul_f32_e32 v13, 0x4f800000, v11
	v_mul_f32_e32 v0, 0xbfb8aa3b, v0
	v_cndmask_b32_e32 v11, v11, v13, vcc
	v_sqrt_f32_e32 v13, v11
	v_exp_f32_e32 v0, v0
	s_mov_b32 s15, 0xbfb8aa3b
	v_add_u32_e32 v14, -1, v13
	v_fma_f32 v15, -v14, v13, v11
	v_cmp_ge_f32_e64 s[40:41], 0, v15
	v_add_u32_e32 v15, 1, v13
	v_add_f32_e32 v0, 1.0, v0
	v_cndmask_b32_e64 v14, v13, v14, s[40:41]
	v_fma_f32 v13, -v15, v13, v11
	v_cmp_lt_f32_e64 s[40:41], 0, v13
	v_rcp_f32_e32 v0, v0
	s_nop 0
	v_cndmask_b32_e64 v13, v14, v15, s[40:41]
	v_mul_f32_e32 v14, 0x37800000, v13
	v_cndmask_b32_e32 v13, v13, v14, vcc
	v_cmp_class_f32_e32 vcc, v11, v230
	s_nop 1
	v_cndmask_b32_e32 v11, v13, v11, vcc
	ds_read_b32 v13, v10 offset:20992
	v_mul_f32_e32 v0, v0, v11
	s_waitcnt lgkmcnt(0)
	v_mul_f32_e32 v0, v13, v0
	ds_write2st64_b32 v10, v0, v12 offset0:82 offset1:210
	v_mov_b32_e32 v10, v66
	v_mov_b32_e32 v0, v69
	v_mov_b32_e32 v11, v72
	s_waitcnt vmcnt(0)
	v_mul_f32_e64 v12, |v11|, s15
	v_exp_f32_e32 v12, v12
	s_mov_b32 s15, 0x3cf5c28f
	v_cmp_ngt_f32_e32 vcc, s15, v12
	s_and_saveexec_b64 s[20:21], vcc
	s_xor_b64 s[20:21], exec, s[20:21]
	s_cbranch_execz .LBB0_703
	v_add_f32_e32 v12, 1.0, v12
	s_mov_b32 s15, 0x800000
	v_cmp_gt_f32_e32 vcc, s15, v12
	s_mov_b32 s15, 0x3f317217
	s_nop 0
	v_cndmask_b32_e64 v13, 0, 32, vcc
	v_ldexp_f32 v12, v12, v13
	v_log_f32_e32 v12, v12
	s_nop 0
	v_mul_f32_e32 v13, 0x3f317217, v12
	v_fma_f32 v13, v12, s15, -v13
	v_fmac_f32_e32 v13, 0x3377d1cf, v12
	s_mov_b32 s15, 0x7f800000
	v_fmac_f32_e32 v13, 0x3f317217, v12
	v_cmp_lt_f32_e64 s[40:41], |v12|, s15
	s_nop 1
	v_cndmask_b32_e64 v12, v12, v13, s[40:41]
	v_cndmask_b32_e32 v13, 0, v232, vcc
	v_sub_f32_e32 v13, v12, v13
